# EpiResid epilogues (D1, D2, OUT): waitcnt placement - each consumer waits only for the residual loads it reads (counted vmcnt incl. stores issued in between) instead of vmcnt(0) for all sixteen
# baseline (speedup 1.0000x reference)
; __device__ __forceinline__ float bflo(unsigned w) { return __uint_as_float(w << 16); }
; __device__ __forceinline__ float bfhi(unsigned w) { return __uint_as_float(w & 0xffff0000u); }
; __device__ __forceinline__ unsigned pk2(float lo, float hi) { return pg8::cvt_pk_bf16(lo, hi); }
;     __device__ __forceinline__ void operator()(const f32x4 (&acc)[2][2][4][2], const Unit& u, int wr, int wc, int fr, int fq) const {
;     ...
;             for (int gg = 0; gg < 4; ++gg) { const int g = hb * 4 + gg; const size_t offn = (size_t)(row0 + (g >> 2) * 128 + (g & 3) * 16) * D + col0;
; #pragma unroll
;                 for (int k = 0; k < 4; ++k) rin[gg][k] = *(const u32x2v*)(in + offn + (k >> 1) * 128 + (k & 1) * 16); }
; #pragma unroll
;             for (int gg = 0; gg < 4; ++gg) {
;                 const int g = hb * 4 + gg, ai = g >> 2, m = g & 3, row = row0 + ai * 128 + m * 16;
;                 const size_t off = (size_t)row * D + col0;
;                 float ss = 0.f;
; #pragma unroll
;                 for (int k = 0; k < 4; ++k) { const int bj = k >> 1, n = k & 1; const size_t o = off + bj * 128 + n * 16; const f32x4 a = acc[ai][bj][m][n] * scale; const u32x2v w0 = rin[gg][k];
;                     f32x4 r; r[0] = bflo(w0.x) + a[0]; r[1] = bfhi(w0.x) + a[1]; r[2] = bflo(w0.y) + a[2]; r[3] = bfhi(w0.y) + a[3];
;                     u32x2v w; w.x = pk2(r[0], r[1]); w.y = pk2(r[2], r[3]); *(u32x2v*)(out + o) = w; ss += (r[0] * r[0] + r[1] * r[1]) + (r[2] * r[2] + r[3] * r[3]); }
;                 ss += __shfl_xor(ss, 16); ss += __shfl_xor(ss, 32);
;                 if (fq == 0) part[(ai * 128 + wr * 64 + m * 16 + fr) * 4 + wc] = ss;
.LBB0_398:
	s_lshl_b32 s15, s15, 8
	v_lshl_or_b32 v136, s14, 8, v171
	v_readlane_b32 s90, v251, 12
	v_add_u32_e32 v138, s15, v167
	v_ashrrev_i32_e32 v137, 31, v136
	s_mov_b64 s[56:57], s[12:13]
	s_mov_b32 s92, 0.5
	s_mov_b64 s[70:71], s[46:47]
	v_readlane_b32 s91, v251, 13
	v_lshlrev_b64 v[140:141], 1, v[136:137]
	v_ashrrev_i32_e32 v139, 31, v138
	v_lshlrev_b64 v[142:143], 11, v[138:139]
	v_lshl_add_u64 v[136:137], s[56:57], 0, v[140:141]
	v_lshl_add_u64 v[144:145], v[136:137], 0, v[142:143]
	global_load_dwordx2 v[174:175], v[144:145], off
	global_load_dwordx2 v[176:177], v[144:145], off offset:32
	global_load_dwordx2 v[178:179], v[144:145], off offset:256
	global_load_dwordx2 v[180:181], v[144:145], off offset:288
	v_or_b32_e32 v144, 16, v138
	v_or_b32_e32 v146, 32, v138
	v_or_b32_e32 v150, 48, v138
	v_ashrrev_i32_e32 v145, 31, v144
	v_ashrrev_i32_e32 v147, 31, v146
	v_ashrrev_i32_e32 v151, 31, v150
	v_lshlrev_b64 v[168:169], 11, v[144:145]
	v_lshlrev_b64 v[148:149], 11, v[146:147]
	v_pk_mul_f32 v[182:183], v[128:129], s[92:93] op_sel_hi:[1,0]
	v_pk_mul_f32 v[188:189], v[122:123], s[92:93] op_sel_hi:[1,0]
	v_pk_mul_f32 v[190:191], v[120:121], s[92:93] op_sel_hi:[1,0]
	v_pk_mul_f32 v[192:193], v[118:119], s[92:93] op_sel_hi:[1,0]
	v_lshl_add_u64 v[118:119], s[70:71], 0, v[140:141]
	v_lshlrev_b64 v[128:129], 11, v[150:151]
	v_lshl_add_u64 v[120:121], v[136:137], 0, v[168:169]
	v_lshl_add_u64 v[122:123], v[136:137], 0, v[148:149]
	v_pk_mul_f32 v[184:185], v[126:127], s[92:93] op_sel_hi:[1,0]
	v_pk_mul_f32 v[186:187], v[124:125], s[92:93] op_sel_hi:[1,0]
	v_lshl_add_u64 v[194:195], v[118:119], 0, v[142:143]
	v_lshl_add_u64 v[196:197], v[136:137], 0, v[128:129]
	global_load_dwordx2 v[156:157], v[120:121], off
	global_load_dwordx2 v[154:155], v[120:121], off offset:32
	global_load_dwordx2 v[152:153], v[120:121], off offset:256
	global_load_dwordx2 v[150:151], v[120:121], off offset:288
	global_load_dwordx2 v[146:147], v[122:123], off
	global_load_dwordx2 v[144:145], v[122:123], off offset:32
	global_load_dwordx2 v[142:143], v[122:123], off offset:256
	global_load_dwordx2 v[140:141], v[122:123], off offset:288
	global_load_dwordx2 v[126:127], v[196:197], off
	global_load_dwordx2 v[124:125], v[196:197], off offset:32
	s_nop 0
	global_load_dwordx2 v[122:123], v[196:197], off offset:256
	global_load_dwordx2 v[120:121], v[196:197], off offset:288
	v_pk_mul_f32 v[114:115], v[114:115], s[92:93] op_sel_hi:[1,0]
	v_pk_mul_f32 v[116:117], v[116:117], s[92:93] op_sel_hi:[1,0]
	s_waitcnt lgkmcnt(0)
	s_waitcnt vmcnt(15)
	v_lshlrev_b32_e32 v196, 16, v174
	v_and_b32_e32 v174, 0xffff0000, v174
	v_lshlrev_b32_e32 v197, 16, v175
	v_and_b32_e32 v175, 0xffff0000, v175
	s_waitcnt vmcnt(14)
	v_lshlrev_b32_e32 v198, 16, v176
	v_and_b32_e32 v176, 0xffff0000, v176
	v_lshlrev_b32_e32 v199, 16, v177
	v_and_b32_e32 v177, 0xffff0000, v177
	s_waitcnt vmcnt(13)
	v_lshlrev_b32_e32 v201, 16, v179
	v_and_b32_e32 v179, 0xffff0000, v179
	v_add_f32_e32 v185, v185, v174
	v_add_f32_e32 v183, v183, v175
	v_add_f32_e32 v176, v189, v176
	v_add_f32_e32 v177, v187, v177
	v_add_f32_e32 v184, v184, v196
	v_add_f32_e32 v182, v182, v197
	v_add_f32_e32 v188, v188, v198
	v_add_f32_e32 v186, v186, v199
	v_add_f32_e32 v189, v190, v201
	v_add_f32_e32 v179, v191, v179
	v_cvt_pk_bf16_f32 v174, v184, v185
	v_cvt_pk_bf16_f32 v175, v182, v183
	v_mul_f32_e32 v185, v185, v185
	v_mul_f32_e32 v183, v183, v183
	v_mul_f32_e32 v190, v176, v176
	v_mul_f32_e32 v191, v177, v177
	v_lshlrev_b32_e32 v200, 16, v178
	v_and_b32_e32 v178, 0xffff0000, v178
	v_fmac_f32_e32 v185, v184, v184
	v_fmac_f32_e32 v183, v182, v182
	v_fmac_f32_e32 v190, v188, v188
	v_fmac_f32_e32 v191, v186, v186
	v_add_f32_e32 v178, v193, v178
	global_store_dwordx2 v[194:195], v[174:175], off
	v_cvt_pk_bf16_f32 v174, v188, v176
	v_add_f32_e32 v175, v185, v183
	v_add_f32_e32 v176, v190, v191
	v_add_f32_e32 v187, v192, v200
	v_mul_f32_e32 v192, v178, v178
	v_add_f32_e32 v175, v175, v176
	v_mul_f32_e32 v176, v179, v179
	v_fmac_f32_e32 v192, v187, v187
	v_fmac_f32_e32 v176, v189, v189
	v_add_f32_e32 v176, v192, v176
	v_add_f32_e32 v175, v175, v176
	s_waitcnt vmcnt(13)
	v_lshlrev_b32_e32 v176, 16, v180
	v_add_f32_e32 v176, v114, v176
	v_and_b32_e32 v114, 0xffff0000, v180
	v_add_f32_e32 v180, v115, v114
	v_lshlrev_b32_e32 v114, 16, v181
	v_add_f32_e32 v182, v116, v114
	v_and_b32_e32 v114, 0xffff0000, v181
	v_add_f32_e32 v181, v117, v114
	v_mul_f32_e32 v114, v180, v180
	v_mul_f32_e32 v115, v181, v181
	v_fmac_f32_e32 v114, v176, v176
	v_fmac_f32_e32 v115, v182, v182
	v_add_f32_e32 v114, v114, v115
	v_and_b32_e32 v116, 64, v209
	v_add_f32_e32 v115, v175, v114
	v_xor_b32_e32 v114, 16, v209
	v_add_u32_e32 v117, 64, v116
	v_cmp_lt_i32_e32 vcc, v114, v117
	v_cvt_pk_bf16_f32 v175, v186, v177
	global_store_dwordx2 v[194:195], v[174:175], off offset:32
	v_cvt_pk_bf16_f32 v174, v187, v178
	v_cvt_pk_bf16_f32 v175, v189, v179
	global_store_dwordx2 v[194:195], v[174:175], off offset:256
	v_cndmask_b32_e32 v114, v209, v114, vcc
	v_lshlrev_b32_e32 v114, 2, v114
	ds_bpermute_b32 v116, v114, v115
	v_cvt_pk_bf16_f32 v174, v176, v180
	v_cvt_pk_bf16_f32 v175, v182, v181
	global_store_dwordx2 v[194:195], v[174:175], off offset:288
	s_waitcnt lgkmcnt(0)
	v_add_f32_e32 v116, v115, v116
	v_xor_b32_e32 v115, 32, v209
	v_cmp_lt_i32_e32 vcc, v115, v117
	s_nop 1
	v_cndmask_b32_e32 v115, v209, v115, vcc
	v_lshlrev_b32_e32 v115, 2, v115
	ds_bpermute_b32 v117, v115, v116
	s_and_saveexec_b64 s[70:71], s[40:41]
	s_waitcnt vmcnt(4)
	s_cbranch_execz .LBB0_400
	s_waitcnt lgkmcnt(0)
	v_add_f32_e32 v116, v116, v117
	ds_write_b32 v172, v116

; __device__ __forceinline__ float bflo(unsigned w) { return __uint_as_float(w << 16); }
; __device__ __forceinline__ float bfhi(unsigned w) { return __uint_as_float(w & 0xffff0000u); }
; __device__ __forceinline__ unsigned pk2(float lo, float hi) { return pg8::cvt_pk_bf16(lo, hi); }
;     __device__ __forceinline__ void operator()(const f32x4 (&acc)[2][2][4][2], const Unit& u, int wr, int wc, int fr, int fq) const {
;     ...
;             for (int gg = 0; gg < 4; ++gg) { const int g = hb * 4 + gg; const size_t offn = (size_t)(row0 + (g >> 2) * 128 + (g & 3) * 16) * D + col0;
; #pragma unroll
;                 for (int k = 0; k < 4; ++k) rin[gg][k] = *(const u32x2v*)(in + offn + (k >> 1) * 128 + (k & 1) * 16); }
; #pragma unroll
;             for (int gg = 0; gg < 4; ++gg) {
;                 const int g = hb * 4 + gg, ai = g >> 2, m = g & 3, row = row0 + ai * 128 + m * 16;
;                 const size_t off = (size_t)row * D + col0;
;                 float ss = 0.f;
; #pragma unroll
;                 for (int k = 0; k < 4; ++k) { const int bj = k >> 1, n = k & 1; const size_t o = off + bj * 128 + n * 16; const f32x4 a = acc[ai][bj][m][n] * scale; const u32x2v w0 = rin[gg][k];
;                     f32x4 r; r[0] = bflo(w0.x) + a[0]; r[1] = bfhi(w0.x) + a[1]; r[2] = bflo(w0.y) + a[2]; r[3] = bfhi(w0.y) + a[3];
;                     u32x2v w; w.x = pk2(r[0], r[1]); w.y = pk2(r[2], r[3]); *(u32x2v*)(out + o) = w; ss += (r[0] * r[0] + r[1] * r[1]) + (r[2] * r[2] + r[3] * r[3]); }
;                 ss += __shfl_xor(ss, 16); ss += __shfl_xor(ss, 32);
;                 if (fq == 0) part[(ai * 128 + wr * 64 + m * 16 + fr) * 4 + wc] = ss;
.LBB0_406:
	s_or_b64 exec, exec, vcc
	s_waitcnt lgkmcnt(0)
	v_lshlrev_b64 v[66:67], 11, v[138:139]
	v_lshl_add_u64 v[98:99], v[66:67], 0, s[88:89]
	v_lshl_add_u64 v[68:69], v[136:137], 0, v[98:99]
	global_load_dwordx2 v[102:103], v[68:69], off
	global_load_dwordx2 v[104:105], v[68:69], off offset:32
	global_load_dwordx2 v[100:101], v[68:69], off offset:256
	global_load_dwordx2 v[96:97], v[68:69], off offset:288
	s_mov_b64 s[56:57], 0x48000
	v_lshl_add_u64 v[94:95], v[66:67], 0, s[56:57]
	s_mov_b64 s[56:57], 0x50000
	v_lshl_add_u64 v[84:85], v[66:67], 0, s[56:57]
	s_mov_b64 s[56:57], 0x58000
	v_lshl_add_u64 v[68:69], v[136:137], 0, v[94:95]
	v_lshl_add_u64 v[70:71], v[66:67], 0, s[56:57]
	global_load_dwordx2 v[92:93], v[68:69], off
	global_load_dwordx2 v[90:91], v[68:69], off offset:32
	global_load_dwordx2 v[88:89], v[68:69], off offset:256
	global_load_dwordx2 v[86:87], v[68:69], off offset:288
	v_lshl_add_u64 v[68:69], v[136:137], 0, v[84:85]
	v_lshl_add_u64 v[66:67], v[136:137], 0, v[70:71]
	global_load_dwordx2 v[82:83], v[68:69], off
	global_load_dwordx2 v[80:81], v[68:69], off offset:32
	global_load_dwordx2 v[78:79], v[68:69], off offset:256
	global_load_dwordx2 v[74:75], v[68:69], off offset:288
	global_load_dwordx2 v[76:77], v[66:67], off
	global_load_dwordx2 v[72:73], v[66:67], off offset:32
	s_nop 0
	global_load_dwordx2 v[68:69], v[66:67], off offset:256
	s_nop 0
	global_load_dwordx2 v[66:67], v[66:67], off offset:288
	v_pk_mul_f32 v[62:63], v[62:63], s[92:93]
	v_pk_mul_f32 v[64:65], v[64:65], s[70:71]
	v_lshl_add_u64 v[98:99], v[118:119], 0, v[98:99]
	v_pk_mul_f32 v[58:59], v[58:59], s[92:93]
	v_pk_mul_f32 v[60:61], v[60:61], s[70:71]
	v_pk_mul_f32 v[54:55], v[54:55], s[92:93]
	v_pk_mul_f32 v[56:57], v[56:57], s[70:71]
	v_pk_mul_f32 v[50:51], v[50:51], s[92:93]
	v_pk_mul_f32 v[52:53], v[52:53], s[70:71]
	s_waitcnt lgkmcnt(0)
	s_waitcnt vmcnt(15)
	v_lshlrev_b32_e32 v106, 16, v102
	v_add_f32_e32 v106, v62, v106
	v_and_b32_e32 v62, 0xffff0000, v102
	v_add_f32_e32 v102, v63, v62
	v_lshlrev_b32_e32 v62, 16, v103
	v_add_f32_e32 v64, v64, v62
	v_and_b32_e32 v62, 0xffff0000, v103
	v_add_f32_e32 v65, v65, v62
	v_cvt_pk_bf16_f32 v62, v106, v102
	v_cvt_pk_bf16_f32 v63, v64, v65
	global_store_dwordx2 v[98:99], v[62:63], off
	v_mul_f32_e32 v62, v102, v102
	v_mul_f32_e32 v63, v65, v65
	v_fmac_f32_e32 v62, v106, v106
	v_fmac_f32_e32 v63, v64, v64
	v_add_f32_e32 v62, v62, v63
	s_waitcnt vmcnt(15)
	v_lshlrev_b32_e32 v63, 16, v104
	v_add_f32_e32 v63, v58, v63
	v_and_b32_e32 v58, 0xffff0000, v104
	v_add_f32_e32 v64, v59, v58
	v_lshlrev_b32_e32 v58, 16, v105
	v_add_f32_e32 v60, v60, v58
	v_and_b32_e32 v58, 0xffff0000, v105
	v_add_f32_e32 v61, v61, v58
	v_cvt_pk_bf16_f32 v58, v63, v64
	v_cvt_pk_bf16_f32 v59, v60, v61
	global_store_dwordx2 v[98:99], v[58:59], off offset:32
	v_mul_f32_e32 v58, v64, v64
	v_mul_f32_e32 v59, v61, v61
	v_fmac_f32_e32 v58, v63, v63
	v_fmac_f32_e32 v59, v60, v60
	v_add_f32_e32 v58, v58, v59
	s_waitcnt vmcnt(15)
	v_lshlrev_b32_e32 v59, 16, v100
	v_add_f32_e32 v59, v54, v59
	v_and_b32_e32 v54, 0xffff0000, v100
	v_add_f32_e32 v60, v55, v54
	v_lshlrev_b32_e32 v54, 16, v101
	v_add_f32_e32 v56, v56, v54
	v_and_b32_e32 v54, 0xffff0000, v101
	v_add_f32_e32 v57, v57, v54
	v_cvt_pk_bf16_f32 v54, v59, v60
	v_cvt_pk_bf16_f32 v55, v56, v57
	global_store_dwordx2 v[98:99], v[54:55], off offset:256
	v_mul_f32_e32 v54, v60, v60
	v_mul_f32_e32 v55, v57, v57
	v_fmac_f32_e32 v54, v59, v59
	v_fmac_f32_e32 v55, v56, v56
	v_add_f32_e32 v54, v54, v55
	s_waitcnt vmcnt(15)
	v_lshlrev_b32_e32 v55, 16, v96
	v_add_f32_e32 v55, v50, v55
	v_and_b32_e32 v50, 0xffff0000, v96
	v_add_f32_e32 v56, v51, v50
	v_lshlrev_b32_e32 v50, 16, v97
	v_add_f32_e32 v52, v52, v50
	v_and_b32_e32 v50, 0xffff0000, v97
	v_add_f32_e32 v53, v53, v50
	v_cvt_pk_bf16_f32 v50, v55, v56
	v_cvt_pk_bf16_f32 v51, v52, v53
	global_store_dwordx2 v[98:99], v[50:51], off offset:288
	v_mul_f32_e32 v50, v56, v56
	v_mul_f32_e32 v51, v53, v53
	v_add_f32_e32 v58, v62, v58
	v_fmac_f32_e32 v50, v55, v55
	v_fmac_f32_e32 v51, v52, v52
	v_add_f32_e32 v54, v58, v54
	v_add_f32_e32 v50, v50, v51
	v_add_f32_e32 v50, v54, v50
	ds_bpermute_b32 v51, v114, v50
	s_waitcnt lgkmcnt(0)
	v_add_f32_e32 v50, v50, v51
	ds_bpermute_b32 v51, v115, v50
	s_and_saveexec_b64 s[70:71], s[40:41]
	s_waitcnt vmcnt(4)
	s_cbranch_execz .LBB0_408
	s_waitcnt lgkmcnt(0)
	v_add_f32_e32 v50, v50, v51
	ds_write_b32 v172, v50 offset:2048

; __device__ __forceinline__ float bflo(unsigned w) { return __uint_as_float(w << 16); }
; __device__ __forceinline__ float bfhi(unsigned w) { return __uint_as_float(w & 0xffff0000u); }
; __device__ __forceinline__ unsigned pk2(float lo, float hi) { return pg8::cvt_pk_bf16(lo, hi); }
;     __device__ __forceinline__ void operator()(const f32x4 (&acc)[2][2][4][2], const Unit& u, int wr, int wc, int fr, int fq) const {
;     ...
;             for (int gg = 0; gg < 4; ++gg) { const int g = hb * 4 + gg; const size_t offn = (size_t)(row0 + (g >> 2) * 128 + (g & 3) * 16) * D + col0;
; #pragma unroll
;                 for (int k = 0; k < 4; ++k) rin[gg][k] = *(const u32x2v*)(in + offn + (k >> 1) * 128 + (k & 1) * 16); }
; #pragma unroll
;             for (int gg = 0; gg < 4; ++gg) {
;                 const int g = hb * 4 + gg, ai = g >> 2, m = g & 3, row = row0 + ai * 128 + m * 16;
;                 const size_t off = (size_t)row * D + col0;
;                 float ss = 0.f;
; #pragma unroll
;                 for (int k = 0; k < 4; ++k) { const int bj = k >> 1, n = k & 1; const size_t o = off + bj * 128 + n * 16; const f32x4 a = acc[ai][bj][m][n] * scale; const u32x2v w0 = rin[gg][k];
;                     f32x4 r; r[0] = bflo(w0.x) + a[0]; r[1] = bfhi(w0.x) + a[1]; r[2] = bflo(w0.y) + a[2]; r[3] = bfhi(w0.y) + a[3];
;                     u32x2v w; w.x = pk2(r[0], r[1]); w.y = pk2(r[2], r[3]); *(u32x2v*)(out + o) = w; ss += (r[0] * r[0] + r[1] * r[1]) + (r[2] * r[2] + r[3] * r[3]); }
;                 ss += __shfl_xor(ss, 16); ss += __shfl_xor(ss, 32);
;                 if (fq == 0) part[(ai * 128 + wr * 64 + m * 16 + fr) * 4 + wc] = ss;
.LBB0_1103:
	s_lshl_b32 s13, s13, 8
	v_lshl_or_b32 v136, s12, 8, v170
	v_readlane_b32 s80, v250, 28
	v_add_u32_e32 v138, s13, v168
	v_ashrrev_i32_e32 v137, 31, v136
	v_readlane_b32 s81, v250, 29
	s_mov_b64 s[56:57], s[46:47]
	s_mov_b64 s[70:71], s[46:47]
	s_mov_b32 s90, 1.0
	v_lshlrev_b64 v[140:141], 1, v[136:137]
	v_ashrrev_i32_e32 v139, 31, v138
	v_lshlrev_b64 v[142:143], 11, v[138:139]
	v_lshl_add_u64 v[136:137], s[56:57], 0, v[140:141]
	v_lshl_add_u64 v[144:145], v[136:137], 0, v[142:143]
	global_load_dwordx2 v[174:175], v[144:145], off
	global_load_dwordx2 v[176:177], v[144:145], off offset:32
	global_load_dwordx2 v[178:179], v[144:145], off offset:256
	global_load_dwordx2 v[180:181], v[144:145], off offset:288
	v_or_b32_e32 v144, 16, v138
	v_or_b32_e32 v146, 32, v138
	v_or_b32_e32 v150, 48, v138
	v_ashrrev_i32_e32 v145, 31, v144
	v_ashrrev_i32_e32 v147, 31, v146
	v_ashrrev_i32_e32 v151, 31, v150
	v_lshlrev_b64 v[166:167], 11, v[144:145]
	v_lshlrev_b64 v[148:149], 11, v[146:147]
	v_pk_mul_f32 v[182:183], v[128:129], s[90:91] op_sel_hi:[1,0]
	v_pk_mul_f32 v[188:189], v[122:123], s[90:91] op_sel_hi:[1,0]
	v_pk_mul_f32 v[190:191], v[120:121], s[90:91] op_sel_hi:[1,0]
	v_pk_mul_f32 v[192:193], v[118:119], s[90:91] op_sel_hi:[1,0]
	v_lshl_add_u64 v[118:119], s[70:71], 0, v[140:141]
	v_lshlrev_b64 v[128:129], 11, v[150:151]
	v_lshl_add_u64 v[120:121], v[136:137], 0, v[166:167]
	v_lshl_add_u64 v[122:123], v[136:137], 0, v[148:149]
	v_pk_mul_f32 v[184:185], v[126:127], s[90:91] op_sel_hi:[1,0]
	v_pk_mul_f32 v[186:187], v[124:125], s[90:91] op_sel_hi:[1,0]
	v_lshl_add_u64 v[194:195], v[118:119], 0, v[142:143]
	v_lshl_add_u64 v[196:197], v[136:137], 0, v[128:129]
	global_load_dwordx2 v[156:157], v[120:121], off
	global_load_dwordx2 v[154:155], v[120:121], off offset:32
	global_load_dwordx2 v[152:153], v[120:121], off offset:256
	global_load_dwordx2 v[150:151], v[120:121], off offset:288
	global_load_dwordx2 v[146:147], v[122:123], off
	global_load_dwordx2 v[144:145], v[122:123], off offset:32
	global_load_dwordx2 v[142:143], v[122:123], off offset:256
	global_load_dwordx2 v[140:141], v[122:123], off offset:288
	global_load_dwordx2 v[126:127], v[196:197], off
	global_load_dwordx2 v[124:125], v[196:197], off offset:32
	s_nop 0
	global_load_dwordx2 v[122:123], v[196:197], off offset:256
	global_load_dwordx2 v[120:121], v[196:197], off offset:288
	v_pk_mul_f32 v[114:115], v[114:115], s[90:91] op_sel_hi:[1,0]
	v_pk_mul_f32 v[116:117], v[116:117], s[90:91] op_sel_hi:[1,0]
	s_waitcnt lgkmcnt(0)
	s_waitcnt vmcnt(15)
	v_lshlrev_b32_e32 v173, 16, v174
	v_and_b32_e32 v174, 0xffff0000, v174
	v_lshlrev_b32_e32 v196, 16, v175
	v_and_b32_e32 v175, 0xffff0000, v175
	s_waitcnt vmcnt(14)
	v_lshlrev_b32_e32 v197, 16, v176
	v_and_b32_e32 v176, 0xffff0000, v176
	v_lshlrev_b32_e32 v198, 16, v177
	v_and_b32_e32 v177, 0xffff0000, v177
	s_waitcnt vmcnt(13)
	v_lshlrev_b32_e32 v200, 16, v179
	v_add_f32_e32 v173, v184, v173
	v_add_f32_e32 v184, v185, v174
	v_add_f32_e32 v183, v183, v175
	v_add_f32_e32 v176, v189, v176
	v_add_f32_e32 v177, v187, v177
	v_add_f32_e32 v182, v182, v196
	v_add_f32_e32 v185, v188, v197
	v_add_f32_e32 v186, v186, v198
	v_add_f32_e32 v188, v190, v200
	v_cvt_pk_bf16_f32 v174, v173, v184
	v_cvt_pk_bf16_f32 v175, v182, v183
	v_mul_f32_e32 v184, v184, v184
	v_mul_f32_e32 v183, v183, v183
	v_mul_f32_e32 v189, v176, v176
	v_mul_f32_e32 v190, v177, v177
	v_lshlrev_b32_e32 v199, 16, v178
	v_and_b32_e32 v178, 0xffff0000, v178
	v_and_b32_e32 v179, 0xffff0000, v179
	v_fmac_f32_e32 v184, v173, v173
	v_fmac_f32_e32 v183, v182, v182
	v_fmac_f32_e32 v189, v185, v185
	v_fmac_f32_e32 v190, v186, v186
	v_add_f32_e32 v178, v193, v178
	v_add_f32_e32 v179, v191, v179
	global_store_dwordx2 v[194:195], v[174:175], off
	v_add_f32_e32 v173, v184, v183
	v_add_f32_e32 v175, v189, v190
	v_add_f32_e32 v187, v192, v199
	v_mul_f32_e32 v191, v178, v178
	v_add_f32_e32 v173, v173, v175
	v_mul_f32_e32 v175, v179, v179
	v_fmac_f32_e32 v191, v187, v187
	v_fmac_f32_e32 v175, v188, v188
	v_add_f32_e32 v175, v191, v175
	v_add_f32_e32 v173, v173, v175
	s_waitcnt vmcnt(13)
	v_lshlrev_b32_e32 v175, 16, v180
	v_cvt_pk_bf16_f32 v174, v185, v176
	v_add_f32_e32 v176, v114, v175
	v_and_b32_e32 v114, 0xffff0000, v180
	v_add_f32_e32 v180, v115, v114
	v_lshlrev_b32_e32 v114, 16, v181
	v_add_f32_e32 v182, v116, v114
	v_and_b32_e32 v114, 0xffff0000, v181
	v_add_f32_e32 v181, v117, v114
	v_mul_f32_e32 v114, v180, v180
	v_mul_f32_e32 v115, v181, v181
	v_fmac_f32_e32 v114, v176, v176
	v_fmac_f32_e32 v115, v182, v182
	v_add_f32_e32 v114, v114, v115
	v_and_b32_e32 v116, 64, v209
	v_add_f32_e32 v115, v173, v114
	v_xor_b32_e32 v114, 16, v209
	v_add_u32_e32 v117, 64, v116
	v_cmp_lt_i32_e32 vcc, v114, v117
	v_cvt_pk_bf16_f32 v175, v186, v177
	global_store_dwordx2 v[194:195], v[174:175], off offset:32
	v_cvt_pk_bf16_f32 v174, v187, v178
	v_cvt_pk_bf16_f32 v175, v188, v179
	global_store_dwordx2 v[194:195], v[174:175], off offset:256
	v_cndmask_b32_e32 v114, v209, v114, vcc
	v_lshlrev_b32_e32 v114, 2, v114
	ds_bpermute_b32 v116, v114, v115
	v_cvt_pk_bf16_f32 v174, v176, v180
	v_cvt_pk_bf16_f32 v175, v182, v181
	global_store_dwordx2 v[194:195], v[174:175], off offset:288
	s_waitcnt lgkmcnt(0)
	v_add_f32_e32 v116, v115, v116
	v_xor_b32_e32 v115, 32, v209
	v_cmp_lt_i32_e32 vcc, v115, v117
	s_nop 1
	v_cndmask_b32_e32 v115, v209, v115, vcc
	v_lshlrev_b32_e32 v115, 2, v115
	ds_bpermute_b32 v117, v115, v116
	s_and_saveexec_b64 s[70:71], s[40:41]
	s_waitcnt vmcnt(4)
	s_cbranch_execz .LBB0_1105
	s_waitcnt lgkmcnt(0)
	v_add_f32_e32 v116, v116, v117
	ds_write_b32 v171, v116

; __device__ __forceinline__ float bflo(unsigned w) { return __uint_as_float(w << 16); }
; __device__ __forceinline__ float bfhi(unsigned w) { return __uint_as_float(w & 0xffff0000u); }
; __device__ __forceinline__ unsigned pk2(float lo, float hi) { return pg8::cvt_pk_bf16(lo, hi); }
;     __device__ __forceinline__ void operator()(const f32x4 (&acc)[2][2][4][2], const Unit& u, int wr, int wc, int fr, int fq) const {
;     ...
;             for (int gg = 0; gg < 4; ++gg) { const int g = hb * 4 + gg; const size_t offn = (size_t)(row0 + (g >> 2) * 128 + (g & 3) * 16) * D + col0;
; #pragma unroll
;                 for (int k = 0; k < 4; ++k) rin[gg][k] = *(const u32x2v*)(in + offn + (k >> 1) * 128 + (k & 1) * 16); }
; #pragma unroll
;             for (int gg = 0; gg < 4; ++gg) {
;                 const int g = hb * 4 + gg, ai = g >> 2, m = g & 3, row = row0 + ai * 128 + m * 16;
;                 const size_t off = (size_t)row * D + col0;
;                 float ss = 0.f;
; #pragma unroll
;                 for (int k = 0; k < 4; ++k) { const int bj = k >> 1, n = k & 1; const size_t o = off + bj * 128 + n * 16; const f32x4 a = acc[ai][bj][m][n] * scale; const u32x2v w0 = rin[gg][k];
;                     f32x4 r; r[0] = bflo(w0.x) + a[0]; r[1] = bfhi(w0.x) + a[1]; r[2] = bflo(w0.y) + a[2]; r[3] = bfhi(w0.y) + a[3];
;                     u32x2v w; w.x = pk2(r[0], r[1]); w.y = pk2(r[2], r[3]); *(u32x2v*)(out + o) = w; ss += (r[0] * r[0] + r[1] * r[1]) + (r[2] * r[2] + r[3] * r[3]); }
;                 ss += __shfl_xor(ss, 16); ss += __shfl_xor(ss, 32);
;                 if (fq == 0) part[(ai * 128 + wr * 64 + m * 16 + fr) * 4 + wc] = ss;
.LBB0_1111:
	s_or_b64 exec, exec, s[92:93]
	s_waitcnt lgkmcnt(0)
	v_lshlrev_b64 v[66:67], 11, v[138:139]
	v_lshl_add_u64 v[98:99], v[66:67], 0, s[88:89]
	v_lshl_add_u64 v[68:69], v[136:137], 0, v[98:99]
	global_load_dwordx2 v[102:103], v[68:69], off
	global_load_dwordx2 v[104:105], v[68:69], off offset:32
	global_load_dwordx2 v[100:101], v[68:69], off offset:256
	global_load_dwordx2 v[96:97], v[68:69], off offset:288
	s_mov_b64 s[56:57], 0x48000
	v_lshl_add_u64 v[94:95], v[66:67], 0, s[56:57]
	s_mov_b64 s[56:57], 0x50000
	v_lshl_add_u64 v[84:85], v[66:67], 0, s[56:57]
	s_mov_b64 s[56:57], 0x58000
	v_lshl_add_u64 v[68:69], v[136:137], 0, v[94:95]
	v_lshl_add_u64 v[70:71], v[66:67], 0, s[56:57]
	global_load_dwordx2 v[92:93], v[68:69], off
	global_load_dwordx2 v[90:91], v[68:69], off offset:32
	global_load_dwordx2 v[88:89], v[68:69], off offset:256
	global_load_dwordx2 v[86:87], v[68:69], off offset:288
	v_lshl_add_u64 v[68:69], v[136:137], 0, v[84:85]
	v_lshl_add_u64 v[66:67], v[136:137], 0, v[70:71]
	global_load_dwordx2 v[82:83], v[68:69], off
	global_load_dwordx2 v[80:81], v[68:69], off offset:32
	global_load_dwordx2 v[78:79], v[68:69], off offset:256
	global_load_dwordx2 v[74:75], v[68:69], off offset:288
	global_load_dwordx2 v[76:77], v[66:67], off
	global_load_dwordx2 v[72:73], v[66:67], off offset:32
	s_nop 0
	global_load_dwordx2 v[68:69], v[66:67], off offset:256
	s_nop 0
	global_load_dwordx2 v[66:67], v[66:67], off offset:288
	v_pk_mul_f32 v[62:63], v[62:63], s[90:91]
	v_pk_mul_f32 v[64:65], v[64:65], s[70:71]
	v_lshl_add_u64 v[98:99], v[118:119], 0, v[98:99]
	v_pk_mul_f32 v[58:59], v[58:59], s[90:91]
	v_pk_mul_f32 v[60:61], v[60:61], s[70:71]
	v_pk_mul_f32 v[54:55], v[54:55], s[90:91]
	v_pk_mul_f32 v[56:57], v[56:57], s[70:71]
	v_pk_mul_f32 v[50:51], v[50:51], s[90:91]
	v_pk_mul_f32 v[52:53], v[52:53], s[70:71]
	s_waitcnt lgkmcnt(0)
	s_waitcnt vmcnt(15)
	v_lshlrev_b32_e32 v106, 16, v102
	v_add_f32_e32 v106, v62, v106
	v_and_b32_e32 v62, 0xffff0000, v102
	v_add_f32_e32 v102, v63, v62
	v_lshlrev_b32_e32 v62, 16, v103
	v_add_f32_e32 v64, v64, v62
	v_and_b32_e32 v62, 0xffff0000, v103
	v_add_f32_e32 v65, v65, v62
	v_cvt_pk_bf16_f32 v62, v106, v102
	v_cvt_pk_bf16_f32 v63, v64, v65
	global_store_dwordx2 v[98:99], v[62:63], off
	v_mul_f32_e32 v62, v102, v102
	v_mul_f32_e32 v63, v65, v65
	v_fmac_f32_e32 v62, v106, v106
	v_fmac_f32_e32 v63, v64, v64
	v_add_f32_e32 v62, v62, v63
	s_waitcnt vmcnt(15)
	v_lshlrev_b32_e32 v63, 16, v104
	v_add_f32_e32 v63, v58, v63
	v_and_b32_e32 v58, 0xffff0000, v104
	v_add_f32_e32 v64, v59, v58
	v_lshlrev_b32_e32 v58, 16, v105
	v_add_f32_e32 v60, v60, v58
	v_and_b32_e32 v58, 0xffff0000, v105
	v_add_f32_e32 v61, v61, v58
	v_cvt_pk_bf16_f32 v58, v63, v64
	v_cvt_pk_bf16_f32 v59, v60, v61
	global_store_dwordx2 v[98:99], v[58:59], off offset:32
	v_mul_f32_e32 v58, v64, v64
	v_mul_f32_e32 v59, v61, v61
	v_fmac_f32_e32 v58, v63, v63
	v_fmac_f32_e32 v59, v60, v60
	v_add_f32_e32 v58, v58, v59
	s_waitcnt vmcnt(15)
	v_lshlrev_b32_e32 v59, 16, v100
	v_add_f32_e32 v59, v54, v59
	v_and_b32_e32 v54, 0xffff0000, v100
	v_add_f32_e32 v60, v55, v54
	v_lshlrev_b32_e32 v54, 16, v101
	v_add_f32_e32 v56, v56, v54
	v_and_b32_e32 v54, 0xffff0000, v101
	v_add_f32_e32 v57, v57, v54
	v_cvt_pk_bf16_f32 v54, v59, v60
	v_cvt_pk_bf16_f32 v55, v56, v57
	global_store_dwordx2 v[98:99], v[54:55], off offset:256
	v_mul_f32_e32 v54, v60, v60
	v_mul_f32_e32 v55, v57, v57
	v_fmac_f32_e32 v54, v59, v59
	v_fmac_f32_e32 v55, v56, v56
	v_add_f32_e32 v54, v54, v55
	s_waitcnt vmcnt(15)
	v_lshlrev_b32_e32 v55, 16, v96
	v_add_f32_e32 v55, v50, v55
	v_and_b32_e32 v50, 0xffff0000, v96
	v_add_f32_e32 v56, v51, v50
	v_lshlrev_b32_e32 v50, 16, v97
	v_add_f32_e32 v52, v52, v50
	v_and_b32_e32 v50, 0xffff0000, v97
	v_add_f32_e32 v53, v53, v50
	v_cvt_pk_bf16_f32 v50, v55, v56
	v_cvt_pk_bf16_f32 v51, v52, v53
	global_store_dwordx2 v[98:99], v[50:51], off offset:288
	v_mul_f32_e32 v50, v56, v56
	v_mul_f32_e32 v51, v53, v53
	v_add_f32_e32 v58, v62, v58
	v_fmac_f32_e32 v50, v55, v55
	v_fmac_f32_e32 v51, v52, v52
	v_add_f32_e32 v54, v58, v54
	v_add_f32_e32 v50, v50, v51
	v_add_f32_e32 v50, v54, v50
	ds_bpermute_b32 v51, v114, v50
	s_waitcnt lgkmcnt(0)
	v_add_f32_e32 v50, v50, v51
	ds_bpermute_b32 v51, v115, v50
	s_and_saveexec_b64 s[70:71], s[40:41]
	s_waitcnt vmcnt(4)
	s_cbranch_execz .LBB0_1113
	s_waitcnt lgkmcnt(0)
	v_add_f32_e32 v50, v50, v51
	ds_write_b32 v171, v50 offset:2048

; __device__ __forceinline__ float bflo(unsigned w) { return __uint_as_float(w << 16); }
; __device__ __forceinline__ float bfhi(unsigned w) { return __uint_as_float(w & 0xffff0000u); }
; __device__ __forceinline__ unsigned pk2(float lo, float hi) { return pg8::cvt_pk_bf16(lo, hi); }
;     __device__ __forceinline__ void operator()(const f32x4 (&acc)[2][2][4][2], const Unit& u, int wr, int wc, int fr, int fq) const {
;     ...
;             for (int gg = 0; gg < 4; ++gg) { const int g = hb * 4 + gg; const size_t offn = (size_t)(row0 + (g >> 2) * 128 + (g & 3) * 16) * D + col0;
; #pragma unroll
;                 for (int k = 0; k < 4; ++k) rin[gg][k] = *(const u32x2v*)(in + offn + (k >> 1) * 128 + (k & 1) * 16); }
; #pragma unroll
;             for (int gg = 0; gg < 4; ++gg) {
;                 const int g = hb * 4 + gg, ai = g >> 2, m = g & 3, row = row0 + ai * 128 + m * 16;
;                 const size_t off = (size_t)row * D + col0;
;                 float ss = 0.f;
; #pragma unroll
;                 for (int k = 0; k < 4; ++k) { const int bj = k >> 1, n = k & 1; const size_t o = off + bj * 128 + n * 16; const f32x4 a = acc[ai][bj][m][n] * scale; const u32x2v w0 = rin[gg][k];
;                     f32x4 r; r[0] = bflo(w0.x) + a[0]; r[1] = bfhi(w0.x) + a[1]; r[2] = bflo(w0.y) + a[2]; r[3] = bfhi(w0.y) + a[3];
;                     u32x2v w; w.x = pk2(r[0], r[1]); w.y = pk2(r[2], r[3]); *(u32x2v*)(out + o) = w; ss += (r[0] * r[0] + r[1] * r[1]) + (r[2] * r[2] + r[3] * r[3]); }
;                 ss += __shfl_xor(ss, 16); ss += __shfl_xor(ss, 32);
;                 if (fq == 0) part[(ai * 128 + wr * 64 + m * 16 + fr) * 4 + wc] = ss;
.LBB0_1271:
	s_lshl_b32 s13, s13, 8
	v_lshl_or_b32 v136, s12, 8, v170
	v_readlane_b32 s80, v251, 12
	v_add_u32_e32 v138, s13, v168
	v_ashrrev_i32_e32 v137, 31, v136
	s_mov_b64 s[56:57], s[46:47]
	s_mov_b64 s[70:71], s[46:47]
	s_mov_b32 s90, 0.5
	v_readlane_b32 s81, v251, 13
	v_lshlrev_b64 v[140:141], 1, v[136:137]
	v_ashrrev_i32_e32 v139, 31, v138
	v_lshlrev_b64 v[142:143], 11, v[138:139]
	v_lshl_add_u64 v[136:137], s[56:57], 0, v[140:141]
	v_lshl_add_u64 v[144:145], v[136:137], 0, v[142:143]
	global_load_dwordx2 v[174:175], v[144:145], off
	global_load_dwordx2 v[176:177], v[144:145], off offset:32
	global_load_dwordx2 v[178:179], v[144:145], off offset:256
	global_load_dwordx2 v[180:181], v[144:145], off offset:288
	v_or_b32_e32 v144, 16, v138
	v_or_b32_e32 v146, 32, v138
	v_or_b32_e32 v150, 48, v138
	v_ashrrev_i32_e32 v145, 31, v144
	v_ashrrev_i32_e32 v147, 31, v146
	v_ashrrev_i32_e32 v151, 31, v150
	v_lshlrev_b64 v[166:167], 11, v[144:145]
	v_lshlrev_b64 v[148:149], 11, v[146:147]
	v_pk_mul_f32 v[182:183], v[128:129], s[90:91] op_sel_hi:[1,0]
	v_pk_mul_f32 v[188:189], v[122:123], s[90:91] op_sel_hi:[1,0]
	v_pk_mul_f32 v[190:191], v[120:121], s[90:91] op_sel_hi:[1,0]
	v_pk_mul_f32 v[192:193], v[118:119], s[90:91] op_sel_hi:[1,0]
	v_lshl_add_u64 v[118:119], s[70:71], 0, v[140:141]
	v_lshlrev_b64 v[128:129], 11, v[150:151]
	v_lshl_add_u64 v[120:121], v[136:137], 0, v[166:167]
	v_lshl_add_u64 v[122:123], v[136:137], 0, v[148:149]
	v_pk_mul_f32 v[184:185], v[126:127], s[90:91] op_sel_hi:[1,0]
	v_pk_mul_f32 v[186:187], v[124:125], s[90:91] op_sel_hi:[1,0]
	v_lshl_add_u64 v[194:195], v[118:119], 0, v[142:143]
	v_lshl_add_u64 v[196:197], v[136:137], 0, v[128:129]
	global_load_dwordx2 v[156:157], v[120:121], off
	global_load_dwordx2 v[154:155], v[120:121], off offset:32
	global_load_dwordx2 v[152:153], v[120:121], off offset:256
	global_load_dwordx2 v[150:151], v[120:121], off offset:288
	global_load_dwordx2 v[146:147], v[122:123], off
	global_load_dwordx2 v[144:145], v[122:123], off offset:32
	global_load_dwordx2 v[142:143], v[122:123], off offset:256
	global_load_dwordx2 v[140:141], v[122:123], off offset:288
	global_load_dwordx2 v[126:127], v[196:197], off
	global_load_dwordx2 v[124:125], v[196:197], off offset:32
	s_nop 0
	global_load_dwordx2 v[122:123], v[196:197], off offset:256
	global_load_dwordx2 v[120:121], v[196:197], off offset:288
	v_pk_mul_f32 v[114:115], v[114:115], s[90:91] op_sel_hi:[1,0]
	v_pk_mul_f32 v[116:117], v[116:117], s[90:91] op_sel_hi:[1,0]
	s_waitcnt lgkmcnt(0)
	s_waitcnt vmcnt(15)
	v_lshlrev_b32_e32 v173, 16, v174
	v_and_b32_e32 v174, 0xffff0000, v174
	v_lshlrev_b32_e32 v196, 16, v175
	v_and_b32_e32 v175, 0xffff0000, v175
	s_waitcnt vmcnt(14)
	v_lshlrev_b32_e32 v197, 16, v176
	v_and_b32_e32 v176, 0xffff0000, v176
	v_lshlrev_b32_e32 v198, 16, v177
	v_and_b32_e32 v177, 0xffff0000, v177
	s_waitcnt vmcnt(13)
	v_lshlrev_b32_e32 v200, 16, v179
	v_add_f32_e32 v173, v184, v173
	v_add_f32_e32 v184, v185, v174
	v_add_f32_e32 v183, v183, v175
	v_add_f32_e32 v176, v189, v176
	v_add_f32_e32 v177, v187, v177
	v_add_f32_e32 v182, v182, v196
	v_add_f32_e32 v185, v188, v197
	v_add_f32_e32 v186, v186, v198
	v_add_f32_e32 v188, v190, v200
	v_cvt_pk_bf16_f32 v174, v173, v184
	v_cvt_pk_bf16_f32 v175, v182, v183
	v_mul_f32_e32 v184, v184, v184
	v_mul_f32_e32 v183, v183, v183
	v_mul_f32_e32 v189, v176, v176
	v_mul_f32_e32 v190, v177, v177
	v_lshlrev_b32_e32 v199, 16, v178
	v_and_b32_e32 v178, 0xffff0000, v178
	v_and_b32_e32 v179, 0xffff0000, v179
	v_fmac_f32_e32 v184, v173, v173
	v_fmac_f32_e32 v183, v182, v182
	v_fmac_f32_e32 v189, v185, v185
	v_fmac_f32_e32 v190, v186, v186
	v_add_f32_e32 v178, v193, v178
	v_add_f32_e32 v179, v191, v179
	global_store_dwordx2 v[194:195], v[174:175], off
	v_add_f32_e32 v173, v184, v183
	v_add_f32_e32 v175, v189, v190
	v_add_f32_e32 v187, v192, v199
	v_mul_f32_e32 v191, v178, v178
	v_add_f32_e32 v173, v173, v175
	v_mul_f32_e32 v175, v179, v179
	v_fmac_f32_e32 v191, v187, v187
	v_fmac_f32_e32 v175, v188, v188
	v_add_f32_e32 v175, v191, v175
	v_add_f32_e32 v173, v173, v175
	s_waitcnt vmcnt(13)
	v_lshlrev_b32_e32 v175, 16, v180
	v_cvt_pk_bf16_f32 v174, v185, v176
	v_add_f32_e32 v176, v114, v175
	v_and_b32_e32 v114, 0xffff0000, v180
	v_add_f32_e32 v180, v115, v114
	v_lshlrev_b32_e32 v114, 16, v181
	v_add_f32_e32 v182, v116, v114
	v_and_b32_e32 v114, 0xffff0000, v181
	v_add_f32_e32 v181, v117, v114
	v_mul_f32_e32 v114, v180, v180
	v_mul_f32_e32 v115, v181, v181
	v_fmac_f32_e32 v114, v176, v176
	v_fmac_f32_e32 v115, v182, v182
	v_add_f32_e32 v114, v114, v115
	v_and_b32_e32 v116, 64, v209
	v_add_f32_e32 v115, v173, v114
	v_xor_b32_e32 v114, 16, v209
	v_add_u32_e32 v117, 64, v116
	v_cmp_lt_i32_e32 vcc, v114, v117
	v_cvt_pk_bf16_f32 v175, v186, v177
	global_store_dwordx2 v[194:195], v[174:175], off offset:32
	v_cvt_pk_bf16_f32 v174, v187, v178
	v_cvt_pk_bf16_f32 v175, v188, v179
	global_store_dwordx2 v[194:195], v[174:175], off offset:256
	v_cndmask_b32_e32 v114, v209, v114, vcc
	v_lshlrev_b32_e32 v114, 2, v114
	ds_bpermute_b32 v116, v114, v115
	v_cvt_pk_bf16_f32 v174, v176, v180
	v_cvt_pk_bf16_f32 v175, v182, v181
	global_store_dwordx2 v[194:195], v[174:175], off offset:288
	s_waitcnt lgkmcnt(0)
	v_add_f32_e32 v116, v115, v116
	v_xor_b32_e32 v115, 32, v209
	v_cmp_lt_i32_e32 vcc, v115, v117
	s_nop 1
	v_cndmask_b32_e32 v115, v209, v115, vcc
	v_lshlrev_b32_e32 v115, 2, v115
	ds_bpermute_b32 v117, v115, v116
	s_and_saveexec_b64 s[70:71], s[40:41]
	s_waitcnt vmcnt(4)
	s_cbranch_execz .LBB0_1273
	s_waitcnt lgkmcnt(0)
	v_add_f32_e32 v116, v116, v117
	ds_write_b32 v171, v116
